# dense attention loop back edge rotated: loop-carried copy hoisted above the barrier, single conditional branch back (asm guide 7.11)
# baseline (speedup 1.0000x reference)
; #define SBAR() __builtin_amdgcn_sched_barrier(0)
; #define SLOAD(i, k0) do { const long to_ = (long)(k0) * ldk * 2; const char* vt_ = (const char*)Vh + to_; const char* kt_ = (const char*)Kh + to_; \
;     sr_[i].vs0 = *(const bf16x8*)(vt_ + toff); sr_[i].vs1 = *(const bf16x8*)(vt_ + h32 + toff); \
;     sr_[i].ks0 = *(const bf16x8*)(kt_ + toff); sr_[i].ks1 = *(const bf16x8*)(kt_ + h32 + toff); } while (0)
; #define SWAIT() do { if constexpr (SDEPTH == 2) asm volatile("s_waitcnt vmcnt(4)" ::: "memory"); else asm volatile("s_waitcnt vmcnt(0)" ::: "memory"); } while (0)
; #define RESC(a) do { if (__any((a) < 1.f)) { if (hi == 0) al_l[r32] = (a); asm volatile("s_waitcnt lgkmcnt(0)" ::: "memory"); \
;     for (int d = 0; d < 4; ++d) for (int r = 0; r < 16; ++r) o[d][r] *= al_l[crow(r, hi)]; } } while (0)
; __device__ __forceinline__ void finishSM(f32x16& p0, f32x16& p1, float alpha, float& l_reg, bf16x8& pa0, bf16x8& pa1, bf16x8& pa2, bf16x8& pa3) {
;     ...
;   l_reg = l_reg * alpha + ps;
; template <int MODE, int QMODE> ...
;     ...
;   for (int j = 1; j + 1 < NT; j += 2) {
;     SBAR(); qkt(pB0, pB1, (bf16*)((char*)K_lds + SHM_K), qr, r32, hi);
;     finishSM(pA0, pA1, alA, l_reg, pa0, pa1, pa2, pa3); SBAR();
;     SLOAD(SO, (j + SDEPTH) * KVBLK); SBAR();
;     PVSM(vb0, pB0, pB1, j * KVBLK, mnB, alB);
;     __syncthreads(); SWAIT(); SWRITE(0, SE);
;     RESC(alB); __syncthreads();
;     SBAR(); qkt(pA0, pA1, K_lds, qr, r32, hi);
;     finishSM(pB0, pB1, alB, l_reg, pa0, pa1, pa2, pa3); SBAR();
;     if (SDEPTH == 1 || j + 3 < NT) SLOAD(SE, (j + 1 + SDEPTH) * KVBLK); SBAR();
;     PVSM(vb0 + (int)SHM_V, pA0, pA1, (j + 1) * KVBLK, mnA, alA);
;     __syncthreads(); SWAIT(); SWRITE(1, SO);
;     RESC(alA); __syncthreads();
.LBB0_181:
	v_add_f32_e32 v98, v233, v235
	v_fmac_f32_e32 v98, v234, v215
	v_mov_b32_e32 v234, v236
	v_add_f32_e32 v215, v239, v240
	v_fmac_f32_e32 v215, v98, v238
	v_lshl_add_u64 v[212:213], v[212:213], 0, s[44:45]
	s_and_b64 vcc, exec, s[16:17]
	s_waitcnt lgkmcnt(0)
	s_barrier
	ds_write_b128 v221, v[178:181] offset:16384
	ds_write_b128 v222, v[190:193] offset:16384
	s_cbranch_vccz .LBB0_171
